# GU: next unit's first B1/A fragment LDS reads hoisted to the start of the epilogue (out of the exposed first load segment)
# baseline (speedup 1.0000x reference)
; #define PG8_STAGE(bufoff, gbase, voff) do { _Pragma("unroll") for (int _i = 0; _i < 2; ++_i) \
;         __builtin_amdgcn_global_load_lds((const unsigned*)((const char*)(gbase) + (voff)[_i]), (PG8_LAS unsigned*)(lds + (bufoff) + ldsw + _i * 8192), 16, 0, 0); } while (0)
; #define PG8_LDA(dst, b, h) do { _Pragma("unroll") for (int m = 0; m < 4; ++m) _Pragma("unroll") for (int k = 0; k < 2; ++k) dst[m][k] = *(const PG8_LAS bf16x8*)(lds + PG8_SA(b, h) + aoff + m * 2048 + k * 1024); } while (0)
; #define PG8_LDB(dst, b, h) do { _Pragma("unroll") for (int n = 0; n < 2; ++n) _Pragma("unroll") for (int k = 0; k < 2; ++k) dst[n][k] = *(const PG8_LAS bf16x8*)(lds + PG8_SB(b, h) + boff + n * 2048 + k * 1024); } while (0)
; #define PG8_WAIT_V(n) asm volatile("s_waitcnt vmcnt(" #n ")" ::: "memory")
; #define PG8_WAIT_L(n) asm volatile("s_waitcnt lgkmcnt(" #n ")" ::: "memory")
; #define PG8_BAR __builtin_amdgcn_s_barrier()
; #define PG8_SCHED __builtin_amdgcn_sched_barrier(0)
; template <class Epi, class Sched, bool ALIGN_EPI = false, bool SP2 = true>
; __device__ __forceinline__ void gemm_phase(PG8_LAS unsigned char* lds, const Gemm g, const Sched& S, const Epi& E) {
;     ...
;         const bool has_next = S.next(ui + 1, nxt);
;         const char* nA = has_next ? (const char*)g.A + (size_t)nxt.pm * tstepA + (size_t)nxt.pn * pnA : cA; const char* nB = has_next ? (const char*)g.Bt + (size_t)nxt.pn * tstep : cB;
;         for (int t = 0; t < nt; t += 2) {
;             const bool last = (t == nt - 2);
;             const char* a1 = cA + (size_t)(t + 1) * kstepA;
;             const char* a2 = last ? nA : cA + (size_t)(t + 2) * kstepA; const char* b2 = last ? nB : cB + (size_t)(t + 2) * kstep;
;             const char* a3 = a2 + kstepA; const char* b3 = b2 + kstep;
;             if (last && has_next) S.a_ready(nxt);
;             if constexpr (SP2) {
;             PG8_LDB(B0, 0, 0); PG8_LDB(B1, 0, 1); PG8_SCHED; PG8_LDA(At, 0, 0); PG8_STAGE(PG8_SA(1, 1), a1 + hstepA, voffA);
;             PG8_WAIT_V(8); PG8_WAIT_L(0); PG8_BAR; PG8_MMA(0, 0, At, B0); PG8_MMA(0, 1, At, B1); PG8_BAR; PG8_SCHED;
;             PG8_LDA(At, 0, 1); PG8_STAGE(PG8_SB(0, 0), b2, voffB); PG8_STAGE(PG8_SB(0, 1), b2 + hstep, voffB); PG8_STAGE(PG8_SA(0, 0), a2, voffA);
;             PG8_WAIT_V(8); PG8_WAIT_L(0); PG8_BAR; PG8_MMA(1, 0, At, B0); PG8_MMA(1, 1, At, B1); PG8_BAR; PG8_SCHED;
.LBB0_127:
	s_ashr_i32 s39, s38, 31
	s_lshl_b64 s[6:7], s[38:39], 19
	s_add_u32 s40, s54, s6
	s_addc_u32 s41, s55, s7
	s_and_b64 s[6:7], s[36:37], exec
	s_cselect_b32 s17, s41, s47
	s_cselect_b32 s39, s40, s46
	s_ashr_i32 s25, s24, 31
	s_lshl_b64 s[6:7], s[24:25], 19
	s_add_u32 s42, s26, s6
	s_addc_u32 s43, s27, s7
	s_and_b64 s[6:7], s[36:37], exec
	s_cselect_b32 s25, s43, s49
	s_cselect_b32 s59, s42, s48
	s_add_u32 s46, s46, 0x40080
	s_addc_u32 s47, s47, 0
	s_add_u32 s6, s48, 0x100
	s_addc_u32 s7, s49, 0
	s_mov_b32 s60, -2
	s_waitcnt lgkmcnt(0)
	s_add_u32 s14, s46, 0xfffc0080
	s_addc_u32 s15, s47, -1
	s_add_i32 s70, 0, 0x10000
	s_cmp_eq_u32 s60, 12
	s_cselect_b32 s51, s17, s15
	s_cselect_b32 s50, s39, s14
	v_add_u32_e32 v141, s70, v147
	s_cselect_b32 s49, s25, s7
	s_cselect_b32 s48, s59, s6
	s_add_i32 s71, 0, 0x14000
	ds_read_b128 v[152:155], v141
	ds_read_b128 v[156:159], v141 offset:1024
	ds_read_b128 v[160:163], v141 offset:2048
	ds_read_b128 v[164:167], v141 offset:3072
	s_cmp_lg_u32 s57, 1
	s_cbranch_scc1 .Lgu_s1_nofirst
	v_add_u32_e32 v141, s71, v147
	ds_read_b128 v[168:171], v141
	ds_read_b128 v[172:175], v141 offset:1024
	ds_read_b128 v[176:179], v141 offset:2048
	ds_read_b128 v[180:183], v141 offset:3072
	ds_read_b128 v[184:187], v150
	ds_read_b128 v[188:191], v150 offset:1024
	ds_read_b128 v[200:203], v150 offset:2048
	ds_read_b128 v[204:207], v150 offset:3072
	ds_read_b128 v[208:211], v150 offset:4096
	ds_read_b128 v[212:215], v150 offset:5120
	ds_read_b128 v[216:219], v150 offset:6144
	ds_read_b128 v[220:223], v150 offset:7168
.Lgu_s1_nofirst:
	v_lshl_add_u64 v[148:149], s[46:47], 0, v[136:137]
	s_add_i32 m0, s29, 0xc000
	s_nop 0
	global_load_lds_dwordx4 v[148:149], off
	v_lshl_add_u64 v[148:149], s[46:47], 0, v[138:139]
	s_add_i32 m0, s29, 0xe000
	s_nop 0
	global_load_lds_dwordx4 v[148:149], off
	s_waitcnt vmcnt(12)
	s_waitcnt lgkmcnt(0)
	s_setprio 1
	s_barrier
	v_mfma_f32_16x16x32_bf16 v[120:123], v[152:155], v[184:187], 0
	v_mfma_f32_16x16x32_bf16 v[112:115], v[160:163], v[184:187], 0
	v_mfma_f32_16x16x32_bf16 v[108:111], v[152:155], v[200:203], 0
	v_mfma_f32_16x16x32_bf16 v[96:99], v[160:163], v[200:203], 0
	v_mfma_f32_16x16x32_bf16 v[92:95], v[152:155], v[208:211], 0
	v_mfma_f32_16x16x32_bf16 v[80:83], v[160:163], v[208:211], 0
	v_mfma_f32_16x16x32_bf16 v[76:79], v[152:155], v[216:219], 0
	v_mfma_f32_16x16x32_bf16 v[64:67], v[160:163], v[216:219], 0
	v_mfma_f32_16x16x32_bf16 v[120:123], v[156:159], v[188:191], v[120:123]
	v_mfma_f32_16x16x32_bf16 v[112:115], v[164:167], v[188:191], v[112:115]
	v_mfma_f32_16x16x32_bf16 v[108:111], v[156:159], v[204:207], v[108:111]
	v_mfma_f32_16x16x32_bf16 v[96:99], v[164:167], v[204:207], v[96:99]
	v_mfma_f32_16x16x32_bf16 v[92:95], v[156:159], v[212:215], v[92:95]
	v_mfma_f32_16x16x32_bf16 v[80:83], v[164:167], v[212:215], v[80:83]
	v_mfma_f32_16x16x32_bf16 v[76:79], v[156:159], v[220:223], v[76:79]
	v_mfma_f32_16x16x32_bf16 v[64:67], v[164:167], v[220:223], v[64:67]
	v_mfma_f32_16x16x32_bf16 v[124:127], v[168:171], v[184:187], 0
	v_mfma_f32_16x16x32_bf16 v[116:119], v[176:179], v[184:187], 0
	v_mfma_f32_16x16x32_bf16 v[104:107], v[168:171], v[200:203], 0
	v_mfma_f32_16x16x32_bf16 v[100:103], v[176:179], v[200:203], 0
	v_mfma_f32_16x16x32_bf16 v[88:91], v[168:171], v[208:211], 0
	v_mfma_f32_16x16x32_bf16 v[84:87], v[176:179], v[208:211], 0
	v_mfma_f32_16x16x32_bf16 v[72:75], v[168:171], v[216:219], 0
	v_mfma_f32_16x16x32_bf16 v[68:71], v[176:179], v[216:219], 0
	v_mfma_f32_16x16x32_bf16 v[124:127], v[172:175], v[188:191], v[124:127]
	v_mfma_f32_16x16x32_bf16 v[116:119], v[180:183], v[188:191], v[116:119]
	v_mfma_f32_16x16x32_bf16 v[104:107], v[172:175], v[204:207], v[104:107]
	v_mfma_f32_16x16x32_bf16 v[100:103], v[180:183], v[204:207], v[100:103]
	v_mfma_f32_16x16x32_bf16 v[88:91], v[172:175], v[212:215], v[88:91]
	v_mfma_f32_16x16x32_bf16 v[84:87], v[180:183], v[212:215], v[84:87]
	v_mfma_f32_16x16x32_bf16 v[72:75], v[172:175], v[220:223], v[72:75]
	v_mfma_f32_16x16x32_bf16 v[68:71], v[180:183], v[220:223], v[68:71]
	s_setprio 0
	s_barrier
	s_add_i32 s14, s70, s28
	v_lshl_add_u64 v[148:149], s[48:49], 0, v[132:133]
	s_mov_b32 m0, s14
	ds_read_b128 v[184:187], v150 offset:16384
	ds_read_b128 v[188:191], v150 offset:17408
	ds_read_b128 v[200:203], v150 offset:18432
	ds_read_b128 v[204:207], v150 offset:19456
	ds_read_b128 v[208:211], v150 offset:20480
	ds_read_b128 v[212:215], v150 offset:21504
	ds_read_b128 v[216:219], v150 offset:22528
	ds_read_b128 v[220:223], v150 offset:23552
	global_load_lds_dwordx4 v[148:149], off
	s_add_i32 m0, s14, 0x2000
	v_lshl_add_u64 v[224:225], s[48:49], 0, v[128:129]
	global_load_lds_dwordx4 v[224:225], off
	v_lshl_add_u64 v[234:235], s[50:51], 0, v[130:131]
	v_lshl_add_u64 v[226:227], s[50:51], 0, v[134:135]
	s_mov_b32 m0, s29
	s_nop 0
	global_load_lds_dwordx4 v[226:227], off
	s_mov_b32 m0, s30
	s_nop 0
	global_load_lds_dwordx4 v[234:235], off
	s_cmp_eq_u32 s57, 1
	s_cbranch_scc1 .Lgu_s2_first
	s_waitcnt vmcnt(14)
	s_branch .Lgu_s2_join

; __device__ __forceinline__ float ssq_rs(ssq_t v) { return __builtin_amdgcn_rsqf((float)v * (1.0f / (16777216.0f * 1024.0f)) + RMS_EPS); }
;     __device__ __forceinline__ void operator()(const f32x4 (&acc)[2][2][4][2], const Unit& u, int wr, int wc, int fr, int fq) const {
;         const int row0 = u.pm * BM + wr * 64 + fr, col0 = u.pn * HALF + wc * 32 + 8 * fq;
;         float rsv[2][4]; ssq_t sv[2][4];
; #pragma unroll
;         for (int ai = 0; ai < 2; ++ai)
; #pragma unroll
;             for (int m = 0; m < 4; ++m) sv[ai][m] = ssq[row0 + ai * HALF + m * 16];
; #pragma unroll
;         for (int ai = 0; ai < 2; ++ai)
; #pragma unroll
;             for (int m = 0; m < 4; ++m) rsv[ai][m] = ssq_rs(sv[ai][m]);
;         asm volatile("" ::: "memory");
; #pragma unroll
;         for (int ai = 0; ai < 2; ++ai)
; #pragma unroll
;             for (int m = 0; m < 4; ++m) {
;                 const int row = row0 + ai * HALF + m * 16;
;                 const float rs = rsv[ai][m], nrs = rs * -1.44269504089f, rs2 = rs * rs;
;                 typedef float f32x2 __attribute__((ext_vector_type(2)));
;                 float a[8];
; #pragma unroll
;                 for (int n = 0; n < 2; ++n)
; #pragma unroll
;                     for (int hf = 0; hf < 2; ++hf) {
;                         const f32x2 g2 = (f32x2){acc[ai][0][m][n][2 * hf], acc[ai][0][m][n][2 * hf + 1]}, u2 = (f32x2){acc[ai][1][m][n][2 * hf], acc[ai][1][m][n][2 * hf + 1]};
;                         const f32x2 t = g2 * nrs;
;                         f32x2 e; e.x = __builtin_amdgcn_exp2f(t.x); e.y = __builtin_amdgcn_exp2f(t.y);
;                         const f32x2 d = e + 1.0f;
;                         f32x2 r; r.x = __builtin_amdgcn_rcpf(d.x); r.y = __builtin_amdgcn_rcpf(d.y);
;                         const f32x2 o = (g2 * u2) * (r * rs2);
;                         a[n * 4 + 2 * hf] = o.x; a[n * 4 + 2 * hf + 1] = o.y;
.LBB0_131:
	v_add_u32_e32 v141, 0x14000, v147
	ds_read_b128 v[168:171], v141
	ds_read_b128 v[172:175], v141 offset:1024
	ds_read_b128 v[176:179], v141 offset:2048
	ds_read_b128 v[180:183], v141 offset:3072
	ds_read_b128 v[184:187], v150
	ds_read_b128 v[188:191], v150 offset:1024
	ds_read_b128 v[200:203], v150 offset:2048
	ds_read_b128 v[204:207], v150 offset:3072
	ds_read_b128 v[208:211], v150 offset:4096
	ds_read_b128 v[212:215], v150 offset:5120
	ds_read_b128 v[216:219], v150 offset:6144
	ds_read_b128 v[220:223], v150 offset:7168
	v_pk_mul_f32 v[126:127], v[122:123], v[126:127]
	v_pk_mul_f32 v[118:119], v[114:115], v[118:119]
	s_lshl_b32 s6, s16, 7
	s_or_b32 s6, s6, s35
	s_ashr_i32 s6, s6, 6
	s_mul_i32 s7, s58, 44
	s_add_i32 s6, s6, s7
	s_ashr_i32 s7, s6, 31
	s_lshl_b64 s[6:7], s[6:7], 15
	s_add_u32 s46, s62, s6
	s_addc_u32 s47, s63, s7
	v_pk_mul_f32 v[104:105], v[108:109], v[104:105]
	v_pk_mul_f32 v[106:107], v[110:111], v[106:107]
	v_pk_mul_f32 v[102:103], v[98:99], v[102:103]
	v_pk_mul_f32 v[88:89], v[92:93], v[88:89]
	v_pk_mul_f32 v[90:91], v[94:95], v[90:91]
	v_pk_mul_f32 v[86:87], v[82:83], v[86:87]
	v_pk_mul_f32 v[72:73], v[76:77], v[72:73]
	v_pk_mul_f32 v[74:75], v[78:79], v[74:75]
	v_pk_mul_f32 v[70:71], v[66:67], v[70:71]
	v_pk_mul_f32 v[56:57], v[60:61], v[56:57]
	v_pk_mul_f32 v[58:59], v[62:63], v[58:59]
	v_pk_mul_f32 v[54:55], v[50:51], v[54:55]
	v_pk_mul_f32 v[40:41], v[44:45], v[40:41]
	v_pk_mul_f32 v[42:43], v[46:47], v[42:43]
	v_pk_mul_f32 v[38:39], v[34:35], v[38:39]
	v_pk_mul_f32 v[24:25], v[28:29], v[24:25]
	v_pk_mul_f32 v[26:27], v[30:31], v[26:27]
	v_pk_mul_f32 v[22:23], v[18:19], v[22:23]
	v_pk_mul_f32 v[8:9], v[12:13], v[8:9]
	v_pk_mul_f32 v[10:11], v[14:15], v[10:11]
	v_pk_mul_f32 v[0:1], v[4:5], v[0:1]
	v_pk_mul_f32 v[2:3], v[6:7], v[2:3]
	s_waitcnt vmcnt(0)
	v_mov_b32_e32 v152, v238
	v_mov_b32_e32 v153, v239
	v_mov_b32_e32 v154, v240
	v_mov_b32_e32 v155, v241
	v_mov_b32_e32 v158, v242
	v_mov_b32_e32 v159, v243
	v_mov_b32_e32 v160, v244
	v_mov_b32_e32 v161, v245
	v_mov_b32_e32 v162, v246
	v_mov_b32_e32 v163, v247
	v_mov_b32_e32 v164, v248
	v_mov_b32_e32 v165, v249
	v_mov_b32_e32 v166, v250
	v_mov_b32_e32 v167, v251
	v_mov_b32_e32 v148, v228
	v_mov_b32_e32 v149, v229
	v_ffbh_u32_e32 v141, v153
	v_min_u32_e32 v141, 32, v141
	v_lshlrev_b64 v[152:153], v141, v[152:153]
	v_min_u32_e32 v143, 1, v152
	v_or_b32_e32 v143, v153, v143
	v_cvt_f32_u32_e32 v143, v143
	v_sub_u32_e32 v141, 32, v141
	v_ldexp_f32 v141, v143, v141
	v_ffbh_u32_e32 v143, v155
	v_min_u32_e32 v143, 32, v143
	v_lshlrev_b64 v[152:153], v143, v[154:155]
	v_min_u32_e32 v144, 1, v152
	v_or_b32_e32 v144, v153, v144
	v_cvt_f32_u32_e32 v144, v144
	v_sub_u32_e32 v143, 32, v143
	v_fmamk_f32 v141, v141, 0x2e800000, v193
	v_rsq_f32_e32 v141, v141
	v_ldexp_f32 v143, v144, v143
	v_fmamk_f32 v143, v143, 0x2e800000, v193
	v_rsq_f32_e32 v156, v143
	v_ffbh_u32_e32 v143, v159
	v_min_u32_e32 v143, 32, v143
	v_lshlrev_b64 v[152:153], v143, v[158:159]
	v_min_u32_e32 v144, 1, v152
	v_or_b32_e32 v144, v153, v144
	v_cvt_f32_u32_e32 v144, v144
	v_sub_u32_e32 v143, 32, v143
	v_ldexp_f32 v143, v144, v143
	v_fmamk_f32 v143, v143, 0x2e800000, v193
	v_rsq_f32_e32 v155, v143
	v_ffbh_u32_e32 v143, v161
	v_min_u32_e32 v143, 32, v143
	v_lshlrev_b64 v[152:153], v143, v[160:161]
	v_min_u32_e32 v144, 1, v152
	v_or_b32_e32 v144, v153, v144
	v_cvt_f32_u32_e32 v144, v144
	v_sub_u32_e32 v143, 32, v143
	v_ldexp_f32 v143, v144, v143
	v_fmamk_f32 v143, v143, 0x2e800000, v193
	v_rsq_f32_e32 v154, v143
	v_ffbh_u32_e32 v143, v163
	v_min_u32_e32 v143, 32, v143
	v_lshlrev_b64 v[152:153], v143, v[162:163]
	v_min_u32_e32 v144, 1, v152
	v_or_b32_e32 v144, v153, v144
	v_cvt_f32_u32_e32 v144, v144
	v_sub_u32_e32 v143, 32, v143
	v_ldexp_f32 v143, v144, v143
	v_ffbh_u32_e32 v144, v165
	v_min_u32_e32 v144, 32, v144
	v_lshlrev_b64 v[152:153], v144, v[164:165]
	v_min_u32_e32 v146, 1, v152
	v_or_b32_e32 v146, v153, v146
	v_cvt_f32_u32_e32 v146, v146
	v_sub_u32_e32 v144, 32, v144
	v_fmamk_f32 v143, v143, 0x2e800000, v193
	v_rsq_f32_e32 v143, v143
	v_ldexp_f32 v144, v146, v144
	v_fmamk_f32 v144, v144, 0x2e800000, v193
	v_rsq_f32_e32 v153, v144
	v_ffbh_u32_e32 v144, v167
	v_min_u32_e32 v144, 32, v144
	v_lshlrev_b64 v[158:159], v144, v[166:167]
	v_min_u32_e32 v146, 1, v158
	v_or_b32_e32 v146, v159, v146
	v_cvt_f32_u32_e32 v146, v146
	v_sub_u32_e32 v144, 32, v144
	v_ldexp_f32 v144, v146, v144
	v_fmamk_f32 v144, v144, 0x2e800000, v193
	v_rsq_f32_e32 v152, v144
	v_ffbh_u32_e32 v144, v149
	v_min_u32_e32 v144, 32, v144
	v_lshlrev_b64 v[148:149], v144, v[148:149]
	v_min_u32_e32 v146, 1, v148
	v_or_b32_e32 v146, v149, v146
	v_cvt_f32_u32_e32 v146, v146
	v_sub_u32_e32 v144, 32, v144
	v_ldexp_f32 v144, v146, v144
	v_mul_f32_e32 v146, 0xbfb8aa3b, v141
	v_pk_mul_f32 v[148:149], v[120:121], v[146:147] op_sel_hi:[1,0]
	v_fmamk_f32 v144, v144, 0x2e800000, v193
	v_exp_f32_e32 v148, v148
	v_exp_f32_e32 v149, v149
	v_rsq_f32_e32 v151, v144
	v_mul_f32_e32 v144, v141, v141
	v_pk_mul_f32 v[120:121], v[120:121], v[124:125]
	v_pk_add_f32 v[148:149], v[148:149], 1.0 op_sel_hi:[1,0]
	v_pk_mul_f32 v[122:123], v[122:123], v[146:147] op_sel_hi:[1,0]
	v_rcp_f32_e32 v148, v148
	v_rcp_f32_e32 v149, v149
	v_pk_mul_f32 v[114:115], v[114:115], v[146:147] op_sel_hi:[1,0]
	v_exp_f32_e32 v122, v122
	v_exp_f32_e32 v123, v123
	v_pk_mul_f32 v[124:125], v[144:145], v[148:149] op_sel_hi:[0,1]
	v_pk_mul_f32 v[120:121], v[120:121], v[124:125]
	v_pk_mul_f32 v[124:125], v[112:113], v[146:147] op_sel_hi:[1,0]
	v_exp_f32_e32 v114, v114
	v_exp_f32_e32 v124, v124
	v_exp_f32_e32 v125, v125
	v_exp_f32_e32 v115, v115
	v_pk_add_f32 v[122:123], v[122:123], 1.0 op_sel_hi:[1,0]
; __device__ __forceinline__ unsigned cvt_pk_bf16(float lo, float hi) { unsigned r; asm volatile("v_cvt_pk_bf16_f32 %0, %1, %2" : "=v"(r) : "v"(lo), "v"(hi)); return r; }
;     __device__ __forceinline__ void operator()(const f32x4 (&acc)[2][2][4][2], const Unit& u, int wr, int wc, int fr, int fq) const {
;     ...
;             for (int m = 0; m < 4; ++m) {
;                 const int row = row0 + ai * HALF + m * 16;
;                 const float rs = rsv[ai][m], nrs = rs * -1.44269504089f, rs2 = rs * rs;
;                 typedef float f32x2 __attribute__((ext_vector_type(2)));
;                 float a[8];
; #pragma unroll
;                 for (int n = 0; n < 2; ++n)
; #pragma unroll
;                     for (int hf = 0; hf < 2; ++hf) {
;                         const f32x2 g2 = (f32x2){acc[ai][0][m][n][2 * hf], acc[ai][0][m][n][2 * hf + 1]}, u2 = (f32x2){acc[ai][1][m][n][2 * hf], acc[ai][1][m][n][2 * hf + 1]};
;                         const f32x2 t = g2 * nrs;
;                         f32x2 e; e.x = __builtin_amdgcn_exp2f(t.x); e.y = __builtin_amdgcn_exp2f(t.y);
;                         const f32x2 d = e + 1.0f;
;                         f32x2 r; r.x = __builtin_amdgcn_rcpf(d.x); r.y = __builtin_amdgcn_rcpf(d.y);
;                         const f32x2 o = (g2 * u2) * (r * rs2);
;                         a[n * 4 + 2 * hf] = o.x; a[n * 4 + 2 * hf + 1] = o.y;
;                     }
;                 u32x4 w; w.x = cvt_pk_bf16(a[0], a[1]); w.y = cvt_pk_bf16(a[2], a[3]); w.z = cvt_pk_bf16(a[4], a[5]); w.w = cvt_pk_bf16(a[6], a[7]);
;                 __builtin_nontemporal_store(w, (u32x4*)(O + ((size_t)(u.pm * (ldc >> 6) + (col0 >> 6)) * 256 + (row & 255)) * 64 + (col0 & 63)));
	v_pk_mul_f32 v[112:113], v[112:113], v[116:117]
	v_pk_add_f32 v[124:125], v[124:125], 1.0 op_sel_hi:[1,0]
	v_pk_add_f32 v[114:115], v[114:115], 1.0 op_sel_hi:[1,0]
	v_rcp_f32_e32 v124, v124
	v_rcp_f32_e32 v125, v125
	v_rcp_f32_e32 v122, v122
	v_rcp_f32_e32 v123, v123
	v_rcp_f32_e32 v114, v114
	v_rcp_f32_e32 v115, v115
	v_pk_mul_f32 v[116:117], v[144:145], v[124:125] op_sel_hi:[0,1]
	v_pk_mul_f32 v[122:123], v[144:145], v[122:123] op_sel_hi:[0,1]
	v_pk_mul_f32 v[112:113], v[112:113], v[116:117]
	v_pk_mul_f32 v[114:115], v[144:145], v[114:115] op_sel_hi:[0,1]
	v_pk_mul_f32 v[122:123], v[126:127], v[122:123]
	v_pk_mul_f32 v[118:119], v[118:119], v[114:115]
	v_cvt_pk_bf16_f32 v114, v120, v121
	v_cvt_pk_bf16_f32 v115, v122, v123
	v_cvt_pk_bf16_f32 v116, v112, v113
	v_lshl_add_u64 v[112:113], s[46:47], 0, v[194:195]
	v_mov_b32_e32 v141, v195
	v_lshl_add_u64 v[112:113], v[112:113], 0, v[140:141]
	v_cvt_pk_bf16_f32 v117, v118, v119
	global_store_dwordx4 v[112:113], v[114:117], off nt
	s_nop 1
	v_mul_f32_e32 v114, 0xbfb8aa3b, v156
	v_pk_mul_f32 v[118:119], v[108:109], v[114:115] op_sel_hi:[1,0]
	v_mul_f32_e32 v116, v156, v156
	v_exp_f32_e32 v118, v118
	v_exp_f32_e32 v119, v119
	s_nop 0
	v_pk_add_f32 v[118:119], v[118:119], 1.0 op_sel_hi:[1,0]
	s_nop 0
	v_rcp_f32_e32 v118, v118
	v_rcp_f32_e32 v119, v119
	s_nop 0
	v_pk_mul_f32 v[108:109], v[116:117], v[118:119] op_sel_hi:[0,1]
	v_pk_mul_f32 v[104:105], v[104:105], v[108:109]
	v_pk_mul_f32 v[108:109], v[110:111], v[114:115] op_sel_hi:[1,0]
	s_nop 0
	v_exp_f32_e32 v108, v108
	v_exp_f32_e32 v109, v109
	s_nop 0
	v_pk_add_f32 v[108:109], v[108:109], 1.0 op_sel_hi:[1,0]
	s_nop 0
	v_rcp_f32_e32 v108, v108
	v_rcp_f32_e32 v109, v109
	s_nop 0
	v_pk_mul_f32 v[108:109], v[116:117], v[108:109] op_sel_hi:[0,1]
	v_pk_mul_f32 v[106:107], v[106:107], v[108:109]
	v_pk_mul_f32 v[108:109], v[96:97], v[114:115] op_sel_hi:[1,0]
	v_pk_mul_f32 v[96:97], v[96:97], v[100:101]
	v_exp_f32_e32 v108, v108
	v_exp_f32_e32 v109, v109
	s_nop 0
	v_pk_add_f32 v[108:109], v[108:109], 1.0 op_sel_hi:[1,0]
	s_nop 0
	v_rcp_f32_e32 v108, v108
	v_rcp_f32_e32 v109, v109
	s_nop 0
	v_pk_mul_f32 v[100:101], v[116:117], v[108:109] op_sel_hi:[0,1]
	v_pk_mul_f32 v[100:101], v[96:97], v[100:101]
	v_pk_mul_f32 v[96:97], v[98:99], v[114:115] op_sel_hi:[1,0]
	s_nop 0
	v_exp_f32_e32 v96, v96
	v_exp_f32_e32 v97, v97
	s_nop 0
	v_pk_add_f32 v[96:97], v[96:97], 1.0 op_sel_hi:[1,0]
	s_nop 0
	v_rcp_f32_e32 v96, v96
	v_rcp_f32_e32 v97, v97
	s_nop 0
	v_pk_mul_f32 v[96:97], v[116:117], v[96:97] op_sel_hi:[0,1]
	v_pk_mul_f32 v[102:103], v[102:103], v[96:97]
	v_cvt_pk_bf16_f32 v96, v104, v105
	v_cvt_pk_bf16_f32 v97, v106, v107
	v_cvt_pk_bf16_f32 v98, v100, v101
	s_nop 0
	v_cvt_pk_bf16_f32 v99, v102, v103
	global_store_dwordx4 v[112:113], v[96:99], off offset:2048 nt
	s_nop 1
	v_mul_f32_e32 v96, 0xbfb8aa3b, v155
	v_pk_mul_f32 v[100:101], v[92:93], v[96:97] op_sel_hi:[1,0]
	v_mul_f32_e32 v98, v155, v155
	v_exp_f32_e32 v100, v100
	v_exp_f32_e32 v101, v101
	s_nop 0
	v_pk_add_f32 v[100:101], v[100:101], 1.0 op_sel_hi:[1,0]
	s_nop 0
	v_rcp_f32_e32 v100, v100
	v_rcp_f32_e32 v101, v101
	s_nop 0
	v_pk_mul_f32 v[92:93], v[98:99], v[100:101] op_sel_hi:[0,1]
	v_pk_mul_f32 v[88:89], v[88:89], v[92:93]
	v_pk_mul_f32 v[92:93], v[94:95], v[96:97] op_sel_hi:[1,0]
	s_nop 0
	v_exp_f32_e32 v92, v92
	v_exp_f32_e32 v93, v93
	s_nop 0
	v_pk_add_f32 v[92:93], v[92:93], 1.0 op_sel_hi:[1,0]
	s_nop 0
	v_rcp_f32_e32 v92, v92
	v_rcp_f32_e32 v93, v93
	s_nop 0
	v_pk_mul_f32 v[92:93], v[98:99], v[92:93] op_sel_hi:[0,1]
	v_pk_mul_f32 v[90:91], v[90:91], v[92:93]
	v_pk_mul_f32 v[92:93], v[80:81], v[96:97] op_sel_hi:[1,0]
	v_pk_mul_f32 v[80:81], v[80:81], v[84:85]
	v_exp_f32_e32 v92, v92
	v_exp_f32_e32 v93, v93
	s_nop 0
	v_pk_add_f32 v[92:93], v[92:93], 1.0 op_sel_hi:[1,0]
	s_nop 0
	v_rcp_f32_e32 v92, v92
	v_rcp_f32_e32 v93, v93
	s_nop 0
	v_pk_mul_f32 v[84:85], v[98:99], v[92:93] op_sel_hi:[0,1]
	v_pk_mul_f32 v[84:85], v[80:81], v[84:85]
	v_pk_mul_f32 v[80:81], v[82:83], v[96:97] op_sel_hi:[1,0]
	s_nop 0
	v_exp_f32_e32 v80, v80
	v_exp_f32_e32 v81, v81
	s_nop 0
	v_pk_add_f32 v[80:81], v[80:81], 1.0 op_sel_hi:[1,0]
	s_nop 0
	v_rcp_f32_e32 v80, v80
	v_rcp_f32_e32 v81, v81
	s_nop 0
	v_pk_mul_f32 v[80:81], v[98:99], v[80:81] op_sel_hi:[0,1]
	v_pk_mul_f32 v[86:87], v[86:87], v[80:81]
	v_cvt_pk_bf16_f32 v80, v88, v89
	v_cvt_pk_bf16_f32 v81, v90, v91
	v_cvt_pk_bf16_f32 v82, v84, v85
	v_add_co_u32_e32 v84, vcc, s23, v112
	v_cvt_pk_bf16_f32 v83, v86, v87
	s_nop 1
	v_addc_co_u32_e32 v85, vcc, 0, v113, vcc
	global_store_dwordx4 v[84:85], v[80:83], off nt
	s_nop 1
	v_mul_f32_e32 v80, 0xbfb8aa3b, v154
	v_pk_mul_f32 v[86:87], v[76:77], v[80:81] op_sel_hi:[1,0]
	v_mul_f32_e32 v82, v154, v154
	v_exp_f32_e32 v86, v86
	v_exp_f32_e32 v87, v87
	s_nop 0
	v_pk_add_f32 v[86:87], v[86:87], 1.0 op_sel_hi:[1,0]
	s_nop 0
	v_rcp_f32_e32 v86, v86
	v_rcp_f32_e32 v87, v87
	s_nop 0
	v_pk_mul_f32 v[76:77], v[82:83], v[86:87] op_sel_hi:[0,1]
	v_pk_mul_f32 v[72:73], v[72:73], v[76:77]
	v_pk_mul_f32 v[76:77], v[78:79], v[80:81] op_sel_hi:[1,0]
	s_nop 0
	v_exp_f32_e32 v76, v76
	v_exp_f32_e32 v77, v77
	s_nop 0
	v_pk_add_f32 v[76:77], v[76:77], 1.0 op_sel_hi:[1,0]
	s_nop 0
	v_rcp_f32_e32 v76, v76
	v_rcp_f32_e32 v77, v77
	s_nop 0
	v_pk_mul_f32 v[76:77], v[82:83], v[76:77] op_sel_hi:[0,1]
	v_pk_mul_f32 v[74:75], v[74:75], v[76:77]
	v_pk_mul_f32 v[76:77], v[64:65], v[80:81] op_sel_hi:[1,0]
	v_pk_mul_f32 v[64:65], v[64:65], v[68:69]
	v_exp_f32_e32 v76, v76
	v_exp_f32_e32 v77, v77
	s_nop 0
	v_pk_add_f32 v[76:77], v[76:77], 1.0 op_sel_hi:[1,0]
	s_nop 0
	v_rcp_f32_e32 v76, v76
	v_rcp_f32_e32 v77, v77
	s_nop 0
	v_pk_mul_f32 v[68:69], v[82:83], v[76:77] op_sel_hi:[0,1]
; __device__ __forceinline__ unsigned cvt_pk_bf16(float lo, float hi) { unsigned r; asm volatile("v_cvt_pk_bf16_f32 %0, %1, %2" : "=v"(r) : "v"(lo), "v"(hi)); return r; }
;     __device__ __forceinline__ void operator()(const f32x4 (&acc)[2][2][4][2], const Unit& u, int wr, int wc, int fr, int fq) const {
;     ...
;             for (int m = 0; m < 4; ++m) {
;                 const int row = row0 + ai * HALF + m * 16;
;                 const float rs = rsv[ai][m], nrs = rs * -1.44269504089f, rs2 = rs * rs;
;                 typedef float f32x2 __attribute__((ext_vector_type(2)));
;                 float a[8];
; #pragma unroll
;                 for (int n = 0; n < 2; ++n)
; #pragma unroll
;                     for (int hf = 0; hf < 2; ++hf) {
;                         const f32x2 g2 = (f32x2){acc[ai][0][m][n][2 * hf], acc[ai][0][m][n][2 * hf + 1]}, u2 = (f32x2){acc[ai][1][m][n][2 * hf], acc[ai][1][m][n][2 * hf + 1]};
;                         const f32x2 t = g2 * nrs;
;                         f32x2 e; e.x = __builtin_amdgcn_exp2f(t.x); e.y = __builtin_amdgcn_exp2f(t.y);
;                         const f32x2 d = e + 1.0f;
;                         f32x2 r; r.x = __builtin_amdgcn_rcpf(d.x); r.y = __builtin_amdgcn_rcpf(d.y);
;                         const f32x2 o = (g2 * u2) * (r * rs2);
;                         a[n * 4 + 2 * hf] = o.x; a[n * 4 + 2 * hf + 1] = o.y;
;                     }
;                 u32x4 w; w.x = cvt_pk_bf16(a[0], a[1]); w.y = cvt_pk_bf16(a[2], a[3]); w.z = cvt_pk_bf16(a[4], a[5]); w.w = cvt_pk_bf16(a[6], a[7]);
;                 __builtin_nontemporal_store(w, (u32x4*)(O + ((size_t)(u.pm * (ldc >> 6) + (col0 >> 6)) * 256 + (row & 255)) * 64 + (col0 & 63)));
	v_pk_mul_f32 v[68:69], v[64:65], v[68:69]
	v_pk_mul_f32 v[64:65], v[66:67], v[80:81] op_sel_hi:[1,0]
	s_nop 0
	v_exp_f32_e32 v64, v64
	v_exp_f32_e32 v65, v65
	s_nop 0
	v_pk_add_f32 v[64:65], v[64:65], 1.0 op_sel_hi:[1,0]
	s_nop 0
	v_rcp_f32_e32 v64, v64
	v_rcp_f32_e32 v65, v65
	s_nop 0
	v_pk_mul_f32 v[64:65], v[82:83], v[64:65] op_sel_hi:[0,1]
	v_pk_mul_f32 v[70:71], v[70:71], v[64:65]
	v_cvt_pk_bf16_f32 v64, v72, v73
	v_cvt_pk_bf16_f32 v65, v74, v75
	v_cvt_pk_bf16_f32 v66, v68, v69
	s_nop 0
	v_cvt_pk_bf16_f32 v67, v70, v71
	global_store_dwordx4 v[84:85], v[64:67], off offset:2048 nt
	s_nop 1
	v_mul_f32_e32 v64, 0xbfb8aa3b, v143
	v_pk_mul_f32 v[68:69], v[60:61], v[64:65] op_sel_hi:[1,0]
	v_mul_f32_e32 v66, v143, v143
	v_exp_f32_e32 v68, v68
	v_exp_f32_e32 v69, v69
	v_pk_mul_f32 v[50:51], v[50:51], v[64:65] op_sel_hi:[1,0]
	v_mov_b32_e32 v143, v195
	v_exp_f32_e32 v50, v50
	v_pk_add_f32 v[68:69], v[68:69], 1.0 op_sel_hi:[1,0]
	v_exp_f32_e32 v51, v51
	v_rcp_f32_e32 v68, v68
	v_rcp_f32_e32 v69, v69
	v_pk_add_f32 v[50:51], v[50:51], 1.0 op_sel_hi:[1,0]
	s_nop 0
	v_rcp_f32_e32 v50, v50
	v_pk_mul_f32 v[60:61], v[66:67], v[68:69] op_sel_hi:[0,1]
	v_pk_mul_f32 v[56:57], v[56:57], v[60:61]
	v_pk_mul_f32 v[60:61], v[62:63], v[64:65] op_sel_hi:[1,0]
	v_rcp_f32_e32 v51, v51
	v_exp_f32_e32 v60, v60
	v_exp_f32_e32 v61, v61
	v_pk_mul_f32 v[50:51], v[66:67], v[50:51] op_sel_hi:[0,1]
	v_pk_mul_f32 v[54:55], v[54:55], v[50:51]
	v_pk_add_f32 v[60:61], v[60:61], 1.0 op_sel_hi:[1,0]
	v_cvt_pk_bf16_f32 v50, v56, v57
	s_nop 0
	v_rcp_f32_e32 v60, v60
	v_rcp_f32_e32 v61, v61
	s_nop 0
	v_pk_mul_f32 v[60:61], v[66:67], v[60:61] op_sel_hi:[0,1]
	v_pk_mul_f32 v[58:59], v[58:59], v[60:61]
	v_pk_mul_f32 v[60:61], v[48:49], v[64:65] op_sel_hi:[1,0]
	v_pk_mul_f32 v[48:49], v[48:49], v[52:53]
	v_exp_f32_e32 v60, v60
	v_exp_f32_e32 v61, v61
	v_cvt_pk_bf16_f32 v51, v58, v59
	s_nop 0
	v_pk_add_f32 v[60:61], v[60:61], 1.0 op_sel_hi:[1,0]
	s_nop 0
	v_rcp_f32_e32 v60, v60
	v_rcp_f32_e32 v61, v61
	s_nop 0
	v_pk_mul_f32 v[52:53], v[66:67], v[60:61] op_sel_hi:[0,1]
	v_pk_mul_f32 v[48:49], v[48:49], v[52:53]
	s_nop 0
	v_cvt_pk_bf16_f32 v52, v48, v49
	v_lshl_add_u64 v[48:49], s[46:47], 0, v[142:143]
	v_lshl_add_u64 v[48:49], v[48:49], 0, v[140:141]
	v_cvt_pk_bf16_f32 v53, v54, v55
	global_store_dwordx4 v[48:49], v[50:53], off nt
	s_mov_b64 s[46:47], -1
	s_nop 0
	v_mul_f32_e32 v50, 0xbfb8aa3b, v153
	v_pk_mul_f32 v[54:55], v[44:45], v[50:51] op_sel_hi:[1,0]
	v_mul_f32_e32 v52, v153, v153
	v_exp_f32_e32 v54, v54
	v_exp_f32_e32 v55, v55
	s_nop 0
	v_pk_add_f32 v[54:55], v[54:55], 1.0 op_sel_hi:[1,0]
	s_nop 0
	v_rcp_f32_e32 v54, v54
	v_rcp_f32_e32 v55, v55
	s_nop 0
	v_pk_mul_f32 v[44:45], v[52:53], v[54:55] op_sel_hi:[0,1]
	v_pk_mul_f32 v[40:41], v[40:41], v[44:45]
	v_pk_mul_f32 v[44:45], v[46:47], v[50:51] op_sel_hi:[1,0]
	s_nop 0
	v_exp_f32_e32 v44, v44
	v_exp_f32_e32 v45, v45
	s_nop 0
	v_pk_add_f32 v[44:45], v[44:45], 1.0 op_sel_hi:[1,0]
	s_nop 0
	v_rcp_f32_e32 v44, v44
	v_rcp_f32_e32 v45, v45
	s_nop 0
	v_pk_mul_f32 v[44:45], v[52:53], v[44:45] op_sel_hi:[0,1]
	v_pk_mul_f32 v[42:43], v[42:43], v[44:45]
	v_pk_mul_f32 v[44:45], v[32:33], v[50:51] op_sel_hi:[1,0]
	v_pk_mul_f32 v[32:33], v[32:33], v[36:37]
	v_exp_f32_e32 v44, v44
	v_exp_f32_e32 v45, v45
	s_nop 0
	v_pk_add_f32 v[44:45], v[44:45], 1.0 op_sel_hi:[1,0]
	s_nop 0
	v_rcp_f32_e32 v44, v44
	v_rcp_f32_e32 v45, v45
	s_nop 0
	v_pk_mul_f32 v[36:37], v[52:53], v[44:45] op_sel_hi:[0,1]
	v_pk_mul_f32 v[36:37], v[32:33], v[36:37]
	v_pk_mul_f32 v[32:33], v[34:35], v[50:51] op_sel_hi:[1,0]
	s_nop 0
	v_exp_f32_e32 v32, v32
	v_exp_f32_e32 v33, v33
	s_nop 0
	v_pk_add_f32 v[32:33], v[32:33], 1.0 op_sel_hi:[1,0]
	s_nop 0
	v_rcp_f32_e32 v32, v32
	v_rcp_f32_e32 v33, v33
	s_nop 0
	v_pk_mul_f32 v[32:33], v[52:53], v[32:33] op_sel_hi:[0,1]
; #define PG8_BAR __builtin_amdgcn_s_barrier()
;     __device__ __forceinline__ void operator()(const f32x4 (&acc)[2][2][4][2], const Unit& u, int wr, int wc, int fr, int fq) const {
;     ...
;             for (int m = 0; m < 4; ++m) {
;                 const int row = row0 + ai * HALF + m * 16;
;                 const float rs = rsv[ai][m], nrs = rs * -1.44269504089f, rs2 = rs * rs;
;                 typedef float f32x2 __attribute__((ext_vector_type(2)));
;                 float a[8];
; #pragma unroll
;                 for (int n = 0; n < 2; ++n)
; #pragma unroll
;                     for (int hf = 0; hf < 2; ++hf) {
;                         const f32x2 g2 = (f32x2){acc[ai][0][m][n][2 * hf], acc[ai][0][m][n][2 * hf + 1]}, u2 = (f32x2){acc[ai][1][m][n][2 * hf], acc[ai][1][m][n][2 * hf + 1]};
;                         const f32x2 t = g2 * nrs;
;                         f32x2 e; e.x = __builtin_amdgcn_exp2f(t.x); e.y = __builtin_amdgcn_exp2f(t.y);
;                         const f32x2 d = e + 1.0f;
;                         f32x2 r; r.x = __builtin_amdgcn_rcpf(d.x); r.y = __builtin_amdgcn_rcpf(d.y);
;                         const f32x2 o = (g2 * u2) * (r * rs2);
;                         a[n * 4 + 2 * hf] = o.x; a[n * 4 + 2 * hf + 1] = o.y;
;                     }
;                 u32x4 w; w.x = cvt_pk_bf16(a[0], a[1]); w.y = cvt_pk_bf16(a[2], a[3]); w.z = cvt_pk_bf16(a[4], a[5]); w.w = cvt_pk_bf16(a[6], a[7]);
;                 __builtin_nontemporal_store(w, (u32x4*)(O + ((size_t)(u.pm * (ldc >> 6) + (col0 >> 6)) * 256 + (row & 255)) * 64 + (col0 & 63)));
;             }
;     }
; template <class Epi, class Sched, bool ALIGN_EPI = false, bool SP2 = true>
; __device__ __forceinline__ void gemm_phase(PG8_LAS unsigned char* lds, const Gemm g, const Sched& S, const Epi& E) {
;     ...
;         if constexpr (ALIGN_EPI) { if (wr == 0) PG8_BAR; }
;         if constexpr (!Epi::AFTER_DRAIN) { E(acc, cur, wr, wc, fr, fq); S.done(cur); }
;         if (!has_next) break;
; #pragma unroll
;         for (int a = 0; a < 2; ++a)
; #pragma unroll
;             for (int b = 0; b < 2; ++b)
; #pragma unroll
;                 for (int m = 0; m < 4; ++m)
; #pragma unroll
;                     for (int n = 0; n < 2; ++n) acc[a][b][m][n] = (f32x4){0.f, 0.f, 0.f, 0.f};
;         cur = nxt; cA = nA; cB = nB; ++ui;
;         if constexpr (ALIGN_EPI) { if (wr == 1) PG8_BAR; }
;     }
	v_pk_mul_f32 v[38:39], v[38:39], v[32:33]
	v_cvt_pk_bf16_f32 v32, v40, v41
	v_cvt_pk_bf16_f32 v33, v42, v43
	v_cvt_pk_bf16_f32 v34, v36, v37
	s_nop 0
	v_cvt_pk_bf16_f32 v35, v38, v39
	global_store_dwordx4 v[48:49], v[32:35], off offset:2048 nt
	s_nop 1
	v_mul_f32_e32 v32, 0xbfb8aa3b, v152
	v_pk_mul_f32 v[36:37], v[28:29], v[32:33] op_sel_hi:[1,0]
	v_mul_f32_e32 v34, v152, v152
	v_exp_f32_e32 v36, v36
	v_exp_f32_e32 v37, v37
	s_nop 0
	v_pk_add_f32 v[36:37], v[36:37], 1.0 op_sel_hi:[1,0]
	s_nop 0
	v_rcp_f32_e32 v36, v36
	v_rcp_f32_e32 v37, v37
	s_nop 0
	v_pk_mul_f32 v[28:29], v[34:35], v[36:37] op_sel_hi:[0,1]
	v_pk_mul_f32 v[24:25], v[24:25], v[28:29]
	v_pk_mul_f32 v[28:29], v[30:31], v[32:33] op_sel_hi:[1,0]
	s_nop 0
	v_exp_f32_e32 v28, v28
	v_exp_f32_e32 v29, v29
	s_nop 0
	v_pk_add_f32 v[28:29], v[28:29], 1.0 op_sel_hi:[1,0]
	s_nop 0
	v_rcp_f32_e32 v28, v28
	v_rcp_f32_e32 v29, v29
	s_nop 0
	v_pk_mul_f32 v[28:29], v[34:35], v[28:29] op_sel_hi:[0,1]
	v_pk_mul_f32 v[26:27], v[26:27], v[28:29]
	v_pk_mul_f32 v[28:29], v[16:17], v[32:33] op_sel_hi:[1,0]
	v_pk_mul_f32 v[16:17], v[16:17], v[20:21]
	v_exp_f32_e32 v28, v28
	v_exp_f32_e32 v29, v29
	s_nop 0
	v_pk_add_f32 v[28:29], v[28:29], 1.0 op_sel_hi:[1,0]
	s_nop 0
	v_rcp_f32_e32 v28, v28
	v_rcp_f32_e32 v29, v29
	s_nop 0
	v_pk_mul_f32 v[20:21], v[34:35], v[28:29] op_sel_hi:[0,1]
	v_pk_mul_f32 v[20:21], v[16:17], v[20:21]
	v_pk_mul_f32 v[16:17], v[18:19], v[32:33] op_sel_hi:[1,0]
	s_nop 0
	v_exp_f32_e32 v16, v16
	v_exp_f32_e32 v17, v17
	s_nop 0
	v_pk_add_f32 v[16:17], v[16:17], 1.0 op_sel_hi:[1,0]
	s_nop 0
	v_rcp_f32_e32 v16, v16
	v_rcp_f32_e32 v17, v17
	s_nop 0
	v_pk_mul_f32 v[16:17], v[34:35], v[16:17] op_sel_hi:[0,1]
	v_pk_mul_f32 v[22:23], v[22:23], v[16:17]
	v_cvt_pk_bf16_f32 v16, v24, v25
	v_cvt_pk_bf16_f32 v17, v26, v27
	v_cvt_pk_bf16_f32 v18, v20, v21
	v_add_co_u32_e32 v20, vcc, s23, v48
	v_cvt_pk_bf16_f32 v19, v22, v23
	s_nop 1
	v_addc_co_u32_e32 v21, vcc, 0, v49, vcc
	global_store_dwordx4 v[20:21], v[16:19], off nt
	s_andn2_b64 vcc, exec, s[36:37]
	s_nop 0
	v_mul_f32_e32 v16, 0xbfb8aa3b, v151
	v_pk_mul_f32 v[22:23], v[12:13], v[16:17] op_sel_hi:[1,0]
	v_mul_f32_e32 v18, v151, v151
	v_exp_f32_e32 v22, v22
	v_exp_f32_e32 v23, v23
	s_nop 0
	v_pk_add_f32 v[22:23], v[22:23], 1.0 op_sel_hi:[1,0]
	s_nop 0
	v_rcp_f32_e32 v22, v22
	v_rcp_f32_e32 v23, v23
	s_nop 0
	v_pk_mul_f32 v[12:13], v[18:19], v[22:23] op_sel_hi:[0,1]
	v_pk_mul_f32 v[8:9], v[8:9], v[12:13]
	v_pk_mul_f32 v[12:13], v[14:15], v[16:17] op_sel_hi:[1,0]
	s_nop 0
	v_exp_f32_e32 v12, v12
	v_exp_f32_e32 v13, v13
	s_nop 0
	v_pk_add_f32 v[12:13], v[12:13], 1.0 op_sel_hi:[1,0]
	s_nop 0
	v_rcp_f32_e32 v12, v12
	v_rcp_f32_e32 v13, v13
	s_nop 0
	v_pk_mul_f32 v[12:13], v[18:19], v[12:13] op_sel_hi:[0,1]
	v_pk_mul_f32 v[10:11], v[10:11], v[12:13]
	v_pk_mul_f32 v[12:13], v[4:5], v[16:17] op_sel_hi:[1,0]
	s_nop 0
	v_exp_f32_e32 v12, v12
	v_exp_f32_e32 v13, v13
	s_nop 0
	v_pk_add_f32 v[12:13], v[12:13], 1.0 op_sel_hi:[1,0]
	s_nop 0
	v_rcp_f32_e32 v12, v12
	v_rcp_f32_e32 v13, v13
	s_nop 0
	v_pk_mul_f32 v[4:5], v[18:19], v[12:13] op_sel_hi:[0,1]
	v_pk_mul_f32 v[4:5], v[0:1], v[4:5]
	v_pk_mul_f32 v[0:1], v[6:7], v[16:17] op_sel_hi:[1,0]
	s_nop 0
	v_exp_f32_e32 v0, v0
	v_exp_f32_e32 v1, v1
	s_nop 0
	v_pk_add_f32 v[0:1], v[0:1], 1.0 op_sel_hi:[1,0]
	s_nop 0
	v_rcp_f32_e32 v0, v0
	v_rcp_f32_e32 v1, v1
	s_nop 0
	v_pk_mul_f32 v[0:1], v[18:19], v[0:1] op_sel_hi:[0,1]
	v_pk_mul_f32 v[6:7], v[2:3], v[0:1]
	v_cvt_pk_bf16_f32 v0, v8, v9
	v_cvt_pk_bf16_f32 v1, v10, v11
	v_cvt_pk_bf16_f32 v2, v4, v5
	s_nop 0
	v_cvt_pk_bf16_f32 v3, v6, v7
	global_store_dwordx4 v[20:21], v[0:3], off offset:2048 nt
	s_cbranch_vccnz .LBB0_124
	s_andn2_b64 vcc, exec, s[0:1]
	s_cbranch_vccnz .LBB0_123
	s_barrier
	s_branch .LBB0_123
